# split barriers 2/3/6: arrival part no longer issues buffer_inv sc1 (the deferred wait carries the acquire where needed)
# speedup vs baseline: 1.0060x; 1.0060x over previous
; __device__ __forceinline__ unsigned xb_add(unsigned* p, unsigned v) { return __hip_atomic_fetch_add(p, v, __ATOMIC_RELAXED, __HIP_MEMORY_SCOPE_AGENT); }
; __device__ __forceinline__ void xcd_barrier(const XcdBarrier& b) {
;     ...
;         const unsigned old = xb_add(&bar[XB_XSUB(b.x)], 1u);
;         const unsigned gen = old / nloc;
;         if (old + 1u == (gen + 1u) * nloc) {
;             __builtin_amdgcn_fence(__ATOMIC_RELEASE, "agent");
;             asm volatile("s_waitcnt vmcnt(0)" ::: "memory");
;             const unsigned og = xb_add(&bar[XB_TOP], 1u);
;             const unsigned tg = og / nx;
;             if (og + 1u == (tg + 1u) * nx) xb_add(&bar[XB_TOPGEN], 1u);
.Lsk2_nl:
.LBB0_214:
	s_andn2_saveexec_b64 s[6:7], s[6:7]
	s_cbranch_execz .LBB0_232
	s_mov_b64 s[6:7], exec
	buffer_wbl2 sc1
	s_waitcnt lgkmcnt(0)
	s_waitcnt vmcnt(0)
	v_mbcnt_lo_u32_b32 v1, s6, 0
	v_mbcnt_hi_u32_b32 v1, s7, v1
	v_cmp_eq_u32_e32 vcc, 0, v1
	s_and_saveexec_b64 s[8:9], vcc
	s_cbranch_execz .LBB0_217
	s_bcnt1_i32_b64 s6, s[6:7]
	v_mov_b32_e32 v2, 0xffc3000
	v_mov_b32_e32 v3, s6
	global_atomic_add v2, v2, v3, s[88:89] offset:1024 sc0

; __device__ __forceinline__ unsigned xb_ld(unsigned* p)              { return __hip_atomic_load(p, __ATOMIC_RELAXED, __HIP_MEMORY_SCOPE_AGENT); }
; __device__ __forceinline__ unsigned xb_add(unsigned* p, unsigned v) { return __hip_atomic_fetch_add(p, v, __ATOMIC_RELAXED, __HIP_MEMORY_SCOPE_AGENT); }
; #define XB_SPIN(cond, bar) do { unsigned _sp = 0; while (cond) { __builtin_amdgcn_s_sleep(1); \
;     if ((++_sp & 255u) == 0u) { if (xb_ld(&(bar)[XB_TMO])) break; if (_sp > XB_SPIN_CAP) { atomicAdd(&(bar)[XB_TMO], 1u); break; } } } } while (0)
; __device__ __forceinline__ void xcd_barrier(const XcdBarrier& b) {
;     ...
;             else XB_SPIN(xb_ld(&bar[XB_TOPGEN]) == tg, bar);
;             __builtin_amdgcn_fence(__ATOMIC_ACQUIRE, "agent");
;             xb_add(&bar[XB_XGEN(b.x)], 1u);
;             asm volatile("s_waitcnt vmcnt(0)" ::: "memory");
.LBB0_231:
	s_or_b64 exec, exec, s[6:7]
	v_mov_b32_e32 v0, 0x2000
	v_mov_b32_e32 v1, 1
	s_waitcnt vmcnt(0)
	s_cmp_eq_u32 s98, 1
	s_cbranch_scc1 .Lsk2_noinv
	buffer_inv sc1
.Lsk2_noinv:
	global_atomic_add v0, v1, s[4:5] offset:1024
	s_waitcnt vmcnt(0)

; __device__ __forceinline__ unsigned xb_ld(unsigned* p)              { return __hip_atomic_load(p, __ATOMIC_RELAXED, __HIP_MEMORY_SCOPE_AGENT); }
; __device__ __forceinline__ unsigned xb_add(unsigned* p, unsigned v) { return __hip_atomic_fetch_add(p, v, __ATOMIC_RELAXED, __HIP_MEMORY_SCOPE_AGENT); }
; #define XB_SPIN(cond, bar) do { unsigned _sp = 0; while (cond) { __builtin_amdgcn_s_sleep(1); \
;     if ((++_sp & 255u) == 0u) { if (xb_ld(&(bar)[XB_TMO])) break; if (_sp > XB_SPIN_CAP) { atomicAdd(&(bar)[XB_TMO], 1u); break; } } } } while (0)
; __device__ __forceinline__ void xcd_barrier(const XcdBarrier& b) {
;     ...
;             else XB_SPIN(xb_ld(&bar[XB_TOPGEN]) == tg, bar);
;             __builtin_amdgcn_fence(__ATOMIC_ACQUIRE, "agent");
;             xb_add(&bar[XB_XGEN(b.x)], 1u);
;             asm volatile("s_waitcnt vmcnt(0)" ::: "memory");
.LBB0_407:
	s_or_b64 exec, exec, s[6:7]
	v_mov_b32_e32 v0, 0x2000
	v_mov_b32_e32 v1, 1
	s_waitcnt vmcnt(0)
	s_cmp_eq_u32 s99, 1
	s_cbranch_scc1 .Lsk3_noinv
	buffer_inv sc1

; __device__ __forceinline__ unsigned xb_add(unsigned* p, unsigned v) { return __hip_atomic_fetch_add(p, v, __ATOMIC_RELAXED, __HIP_MEMORY_SCOPE_AGENT); }
; __device__ __forceinline__ void xcd_barrier(const XcdBarrier& b) {
;     ...
;         const unsigned old = xb_add(&bar[XB_XSUB(b.x)], 1u);
;         const unsigned gen = old / nloc;
;         if (old + 1u == (gen + 1u) * nloc) {
;             __builtin_amdgcn_fence(__ATOMIC_RELEASE, "agent");
;             asm volatile("s_waitcnt vmcnt(0)" ::: "memory");
;             const unsigned og = xb_add(&bar[XB_TOP], 1u);
;             const unsigned tg = og / nx;
;             if (og + 1u == (tg + 1u) * nx) xb_add(&bar[XB_TOPGEN], 1u);
.Lsk6_nl:
.LBB0_734:
	s_andn2_saveexec_b64 s[8:9], s[8:9]
	s_cbranch_execz .LBB0_752
	s_mov_b64 s[8:9], exec
	buffer_wbl2 sc1
	s_waitcnt lgkmcnt(0)
	s_waitcnt vmcnt(0)
	v_mbcnt_lo_u32_b32 v1, s8, 0
	v_mbcnt_hi_u32_b32 v1, s9, v1
	v_cmp_eq_u32_e32 vcc, 0, v1
	s_and_saveexec_b64 s[10:11], vcc
	s_cbranch_execz .LBB0_737
	s_bcnt1_i32_b64 s8, s[8:9]
	v_mov_b32_e32 v2, 0xffc3000
	v_mov_b32_e32 v3, s8
	global_atomic_add v2, v2, v3, s[88:89] offset:1024 sc0

; __device__ __forceinline__ unsigned xb_ld(unsigned* p)              { return __hip_atomic_load(p, __ATOMIC_RELAXED, __HIP_MEMORY_SCOPE_AGENT); }
; __device__ __forceinline__ unsigned xb_add(unsigned* p, unsigned v) { return __hip_atomic_fetch_add(p, v, __ATOMIC_RELAXED, __HIP_MEMORY_SCOPE_AGENT); }
; #define XB_SPIN(cond, bar) do { unsigned _sp = 0; while (cond) { __builtin_amdgcn_s_sleep(1); \
;     if ((++_sp & 255u) == 0u) { if (xb_ld(&(bar)[XB_TMO])) break; if (_sp > XB_SPIN_CAP) { atomicAdd(&(bar)[XB_TMO], 1u); break; } } } } while (0)
; __device__ __forceinline__ void xcd_barrier(const XcdBarrier& b) {
;     ...
;             else XB_SPIN(xb_ld(&bar[XB_TOPGEN]) == tg, bar);
;             __builtin_amdgcn_fence(__ATOMIC_ACQUIRE, "agent");
;             xb_add(&bar[XB_XGEN(b.x)], 1u);
;             asm volatile("s_waitcnt vmcnt(0)" ::: "memory");
.LBB0_751:
	s_or_b64 exec, exec, s[8:9]
	v_mov_b32_e32 v0, 0x2000
	v_mov_b32_e32 v1, 1
	s_waitcnt vmcnt(0)
	s_cmp_eq_u32 s98, 1
	s_cbranch_scc1 .Lsk6_noinv
	buffer_inv sc1
